# diff K-row prefetch addresses kept as incrementally advanced pointers (2 fewer 64-bit multiply-adds and 2 adds per iteration), on top of the previous stack
# speedup vs baseline: 1.0076x; 1.0029x over previous
.LBB0_926:
	s_and_b32 s0, s12, 0x80
	s_lshl_b32 s1, s0, 7
	s_add_i32 s39, s1, 0
	s_lshl_b32 s0, s0, 4
	s_add_i32 s2, s39, s0
	s_cmpk_gt_u32 s38, 0x101
	s_cselect_b64 s[0:1], -1, 0
	s_and_b64 vcc, exec, s[0:1]
	s_waitcnt vmcnt(3)
	ds_write_b128 v244, v[18:21]
	s_waitcnt vmcnt(1)
	ds_write_b128 v245, v[22:25] offset:32768
	s_waitcnt vmcnt(1)
	ds_write_b128 v244, v[26:29] offset:8192
	s_waitcnt vmcnt(0)
	ds_write_b128 v245, v[30:33] offset:41984
	s_waitcnt lgkmcnt(0)
	s_barrier
	ds_read_b128 v[130:133], v246
	ds_read_b128 v[168:171], v246 offset:2048
	s_cbranch_vccnz .LBB0_925
	s_cmp_eq_u32 s12, 0
	s_cbranch_scc0 .Lpf_next_925
	v_add_u32_e32 v250, s36, v161
	v_mad_i64_i32 v[250:251], s[40:41], v250, s21, v[146:147]
	v_add_u32_e32 v252, s37, v161
	v_mad_i64_i32 v[252:253], s[40:41], v252, s21, v[146:147]
	s_sub_i32 s100, s35, s36
	s_mul_hi_i32 s101, s100, 0x1640
	s_mul_i32 s100, s100, 0x1640
	s_branch .Lpf_load_925
.Lpf_next_925:
	v_lshl_add_u64 v[250:251], v[250:251], 0, s[100:101]
	v_lshl_add_u64 v[252:253], v[252:253], 0, s[100:101]
	s_mov_b32 s100, 0xb2000
	s_mov_b32 s101, 0
.Lpf_load_925:
	global_load_dwordx4 v[18:21], v[250:251], off offset:3648
	global_load_dwordx4 v[26:29], v[252:253], off offset:3648
	global_load_dwordx4 v[22:25], v[148:149], off
	global_load_dwordx4 v[30:33], v[148:149], off offset:128
	s_branch .LBB0_925

.LBB0_2160:
	s_and_b32 s0, s10, 0x80
	s_lshl_b32 s1, s0, 7
	s_add_i32 s37, s1, 0
	s_lshl_b32 s0, s0, 4
	s_add_i32 s2, s37, s0
	s_cmpk_gt_u32 s36, 0x101
	s_cselect_b64 s[0:1], -1, 0
	s_and_b64 vcc, exec, s[0:1]
	s_waitcnt vmcnt(3)
	ds_write_b128 v244, v[18:21]
	s_waitcnt vmcnt(1)
	ds_write_b128 v245, v[22:25] offset:32768
	s_waitcnt vmcnt(1)
	ds_write_b128 v244, v[26:29] offset:8192
	s_waitcnt vmcnt(0)
	ds_write_b128 v245, v[30:33] offset:41984
	s_waitcnt lgkmcnt(0)
	s_barrier
	ds_read_b128 v[130:133], v246
	ds_read_b128 v[166:169], v246 offset:2048
	s_cbranch_vccnz .LBB0_2159
	s_cmp_eq_u32 s10, 0
	s_cbranch_scc0 .Lpf_next_2159
	v_add_u32_e32 v250, s34, v159
	v_mad_i64_i32 v[250:251], s[38:39], v250, s19, v[144:145]
	v_add_u32_e32 v252, s35, v159
	v_mad_i64_i32 v[252:253], s[38:39], v252, s19, v[144:145]
	s_sub_i32 s100, s33, s34
	s_mul_hi_i32 s101, s100, 0x1640
	s_mul_i32 s100, s100, 0x1640
	s_branch .Lpf_load_2159

.Lpf_load_2159:
	global_load_dwordx4 v[18:21], v[250:251], off offset:3648
	global_load_dwordx4 v[26:29], v[252:253], off offset:3648
	global_load_dwordx4 v[22:25], v[146:147], off
	global_load_dwordx4 v[30:33], v[146:147], off offset:128
	s_branch .LBB0_2159

	.amdhsa_kernel _Z8mega_fwd4Args
		.amdhsa_group_segment_fixed_size 0
		.amdhsa_private_segment_fixed_size 0
		.amdhsa_kernarg_size 544
		.amdhsa_user_sgpr_count 2
		.amdhsa_user_sgpr_dispatch_ptr 0
		.amdhsa_user_sgpr_queue_ptr 0
		.amdhsa_user_sgpr_kernarg_segment_ptr 1
		.amdhsa_user_sgpr_dispatch_id 0
		.amdhsa_user_sgpr_kernarg_preload_length 0
		.amdhsa_user_sgpr_kernarg_preload_offset 0
		.amdhsa_user_sgpr_private_segment_size 0
		.amdhsa_uses_dynamic_stack 0
		.amdhsa_enable_private_segment 0
		.amdhsa_system_sgpr_workgroup_id_x 1
		.amdhsa_system_sgpr_workgroup_id_y 0
		.amdhsa_system_sgpr_workgroup_id_z 0
		.amdhsa_system_sgpr_workgroup_info 0
		.amdhsa_system_vgpr_workitem_id 2
		.amdhsa_next_free_vgpr 256
		.amdhsa_next_free_sgpr 102
		.amdhsa_accum_offset 256
		.amdhsa_reserve_vcc 1
		.amdhsa_float_round_mode_32 0
		.amdhsa_float_round_mode_16_64 0
		.amdhsa_float_denorm_mode_32 3
		.amdhsa_float_denorm_mode_16_64 3
		.amdhsa_dx10_clamp 1
		.amdhsa_ieee_mode 1
		.amdhsa_fp16_overflow 0
		.amdhsa_tg_split 0
		.amdhsa_exception_fp_ieee_invalid_op 0
		.amdhsa_exception_fp_denorm_src 0
		.amdhsa_exception_fp_ieee_div_zero 0
		.amdhsa_exception_fp_ieee_overflow 0
		.amdhsa_exception_fp_ieee_underflow 0
		.amdhsa_exception_fp_ieee_inexact 0
		.amdhsa_exception_int_div_zero 0
	.end_amdhsa_kernel

amdhsa.kernels:
  - .agpr_count:     0
    .args:
      - .offset:         0
        .size:           288
        .value_kind:     by_value
      - .offset:         288
        .size:           4
        .value_kind:     hidden_block_count_x
      - .offset:         292
        .size:           4
        .value_kind:     hidden_block_count_y
      - .offset:         296
        .size:           4
        .value_kind:     hidden_block_count_z
      - .offset:         300
        .size:           2
        .value_kind:     hidden_group_size_x
      - .offset:         302
        .size:           2
        .value_kind:     hidden_group_size_y
      - .offset:         304
        .size:           2
        .value_kind:     hidden_group_size_z
      - .offset:         306
        .size:           2
        .value_kind:     hidden_remainder_x
      - .offset:         308
        .size:           2
        .value_kind:     hidden_remainder_y
      - .offset:         310
        .size:           2
        .value_kind:     hidden_remainder_z
      - .offset:         328
        .size:           8
        .value_kind:     hidden_global_offset_x
      - .offset:         336
        .size:           8
        .value_kind:     hidden_global_offset_y
      - .offset:         344
        .size:           8
        .value_kind:     hidden_global_offset_z
      - .offset:         352
        .size:           2
        .value_kind:     hidden_grid_dims
      - .offset:         376
        .size:           8
        .value_kind:     hidden_multigrid_sync_arg
      - .offset:         408
        .size:           4
        .value_kind:     hidden_dynamic_lds_size
    .group_segment_fixed_size: 0
    .kernarg_segment_align: 8
    .kernarg_segment_size: 544
    .language:       OpenCL C
    .language_version:
      - 2
      - 0
    .max_flat_workgroup_size: 512
    .name:           _Z8mega_fwd4Args
    .private_segment_fixed_size: 0
    .sgpr_count:     108
    .sgpr_spill_count: 96
    .symbol:         _Z8mega_fwd4Args.kd
    .uniform_work_group_size: 1
    .uses_dynamic_stack: false
    .vgpr_count:     256
    .vgpr_spill_count: 0
    .wavefront_size: 64
